# zero-setprio GEMM phases + one static s_setprio 1 for waves 4-7 during the mixer phase (attention / conv-pool), reset at phase end
# baseline (speedup 1.0000x reference)
; #define LAS __attribute__((address_space(3)))
; __device__ __forceinline__ void sb_attn_wave(const bf16_t* __restrict__ P, const bf16_t* __restrict__ KHp, const bf16_t* __restrict__ Vt, bf16_t* __restrict__ mixed, int gw, int NGW, int lane, LAS unsigned char* wl) {
;     constexpr int NUNITS = NBATCH * 8 * 128;
;     const int r32 = lane & 31, hi = lane >> 5;
;     const int pi = (r32 & 19) | ((r32 & 4) << 1) | ((r32 & 8) >> 1);
;     const int lr = lane >> 3, lp = lane & 7;
;     LAS unsigned char* kl = wl; LAS unsigned char* vl = wl + SB_TILE;
;     const int wofs = lr * SB_PITCH + lp * 16;
;     const int kro = pi * SB_PITCH + hi * 16;
;     const int vro = r32 * SB_PITCH + hi * 16;
;     int u = gw; if (u >= NUNITS) return;
;     size_t tok0; int q0, h, kt; const bf16_t* kg; const bf16_t* vg;
;     bf16x8 qf[4]; u32x4 ks[8], vs[8];
;     ...
;     SB_UNIT_SETUP(u);
.LBB0_404:
	s_cmp_ge_i32 s52, s28
	s_cselect_b64 s[4:5], -1, 0
	s_and_b64 s[0:1], s[4:5], s[0:1]
	s_andn2_b64 vcc, exec, s[0:1]
	s_cbranch_vccnz .LBB0_471
	v_readlane_b32 s100, v254, 2
	s_nop 0
	s_bitcmp1_b32 s100, 2
	s_cbranch_scc0 .Lmix_prio_skip
	s_setprio 1
.Lmix_prio_skip:
	v_readlane_b32 s0, v253, 50
	v_mov_b32_e32 v145, v223
	v_readlane_b32 s1, v253, 51
	s_andn2_b64 vcc, exec, s[0:1]
	v_and_b32_e32 v147, 63, v145
	s_cbranch_vccnz .LBB0_420
	v_lshlrev_b32_e32 v3, 1, v147
	s_waitcnt vmcnt(0)
	v_lshrrev_b32_e32 v4, 1, v145
	v_and_b32_e32 v2, 19, v145
	v_and_b32_e32 v3, 8, v3
	v_and_b32_e32 v4, 4, v4
	v_or3_b32 v3, v2, v3, v4
	v_lshlrev_b32_e32 v2, 4, v145
	s_waitcnt lgkmcnt(0)
	v_lshrrev_b32_e32 v1, 5, v147
	v_lshrrev_b32_e32 v4, 3, v147
	v_and_b32_e32 v2, 0x70, v2
	s_movk_i32 s1, 0x90
	v_readlane_b32 s0, v253, 52
	v_lshlrev_b32_e32 v0, 4, v1
	v_mad_u32_u24 v5, v4, s1, v2
	v_lshlrev_b32_e32 v146, 3, v1
	v_lshlrev_b32_e32 v192, 7, v4
	v_lshlrev_b32_e32 v4, 2, v1
	v_mov_b32_e32 v1, s0
	v_mad_u32_u24 v10, v3, s1, v1
	v_lshl_add_u64 v[6:7], s[20:21], 0, v[192:193]
	v_mov_b32_e32 v3, v193
	v_lshl_add_u64 v[148:149], v[6:7], 0, v[2:3]
	v_lshl_add_u64 v[6:7], s[18:19], 0, v[192:193]
	v_and_b32_e32 v144, 31, v145
	v_lshl_add_u64 v[150:151], v[6:7], 0, v[2:3]
	v_and_b32_e32 v6, 64, v228
	v_readlane_b32 s4, v253, 61
	v_mad_u32_u24 v11, v144, s1, v1
	v_xor_b32_e32 v1, 32, v228
	v_add_u32_e32 v6, 64, v6
	v_readlane_b32 s5, v253, 62
	v_cmp_lt_i32_e32 vcc, v1, v6
	v_readlane_b32 s8, v254, 43
	v_lshl_add_u64 v[6:7], s[4:5], 0, v[192:193]
	v_readlane_b32 s4, v253, 63
	v_readlane_b32 s5, v254, 0
	v_readlane_b32 s1, v253, 54
	v_readlane_b32 s9, v254, 44
	v_lshl_add_u64 v[8:9], s[4:5], 0, v[192:193]
	s_mov_b32 s4, s8
	v_lshl_add_u64 v[154:155], v[8:9], 0, v[2:3]
	v_writelane_b32 v254, s4, 43
	v_or_b32_e32 v8, s1, v144
	v_readlane_b32 s1, v253, 57
	v_writelane_b32 v254, s5, 44
	v_readlane_b32 s4, v253, 59
	v_mov_b32_e32 v9, s1
	v_cndmask_b32_e32 v1, v228, v1, vcc
	v_lshlrev_b64 v[8:9], 12, v[8:9]
	v_readlane_b32 s5, v253, 60
	v_lshlrev_b32_e32 v156, 2, v1
	s_mov_b32 s9, s13
	v_lshl_add_u64 v[8:9], s[4:5], 0, v[8:9]
	v_mov_b32_e32 v1, v193
	v_lshl_add_u64 v[152:153], v[6:7], 0, v[2:3]
	v_lshl_add_u64 v[2:3], v[154:155], 0, s[8:9]
	v_lshl_add_u64 v[8:9], v[8:9], 0, v[0:1]
	s_movk_i32 s1, 0x1000
	global_load_dwordx4 v[64:67], v[8:9], off
	global_load_dwordx4 v[68:71], v[8:9], off offset:32
	s_waitcnt lgkmcnt(0)
	global_load_dwordx4 v[72:75], v[8:9], off offset:64
	global_load_dwordx4 v[76:79], v[8:9], off offset:96
	global_load_dwordx4 v[80:83], v[2:3], off
	global_load_dwordx4 v[84:87], v[2:3], off offset:1024
	global_load_dwordx4 v[88:91], v[2:3], off offset:2048
	global_load_dwordx4 v[92:95], v[2:3], off offset:3072
	v_add_co_u32_e32 v2, vcc, s1, v2
	v_lshl_add_u64 v[6:7], v[152:153], 0, s[8:9]
	s_nop 0
	v_addc_co_u32_e32 v3, vcc, 0, v3, vcc
	global_load_dwordx4 v[96:99], v[2:3], off
	global_load_dwordx4 v[100:103], v[2:3], off offset:1024
	global_load_dwordx4 v[104:107], v[2:3], off offset:2048
	global_load_dwordx4 v[108:111], v[2:3], off offset:3072
	global_load_dwordx4 v[112:115], v[6:7], off
	global_load_dwordx4 v[116:119], v[6:7], off offset:1024
	global_load_dwordx4 v[120:123], v[6:7], off offset:2048
	global_load_dwordx4 v[124:127], v[6:7], off offset:3072
	v_add_co_u32_e32 v2, vcc, 0x1000, v6
	v_add_u32_e32 v157, s0, v5
	s_nop 0
	v_addc_co_u32_e32 v3, vcc, 0, v7, vcc
	global_load_dwordx4 v[128:131], v[2:3], off
	global_load_dwordx4 v[132:135], v[2:3], off offset:1024
	global_load_dwordx4 v[136:139], v[2:3], off offset:2048
	global_load_dwordx4 v[140:143], v[2:3], off offset:3072
	v_readlane_b32 s0, v253, 55
	v_cmp_gt_u32_e64 s[6:7], 32, v147
	v_lshlrev_b32_e32 v192, 1, v4
	v_add_u32_e32 v158, v10, v0
	v_add_u32_e32 v159, v11, v0
	v_readlane_b32 s38, v254, 1
	v_readlane_b32 s39, v253, 58
	v_readlane_b32 s48, v253, 53
	v_readlane_b32 s1, v253, 56
	v_readlane_b32 s49, v254, 2
	s_branch .LBB0_408

; __device__ __forceinline__ bool is_thread0(int wave0) { return wave0 == 0 && __builtin_amdgcn_mbcnt_hi(~0u, __builtin_amdgcn_mbcnt_lo(~0u, 0u)) == 0u; }
; __device__ __forceinline__ void xcd_barrier(const XcdBarrier& b, int wave0) {
;     asm volatile("s_waitcnt vmcnt(0)" ::: "memory");
;     __syncthreads();
;     if (is_thread0(wave0)) {
;         unsigned* bar = b.bar;
;         __builtin_amdgcn_s_waitcnt(0);
;         unsigned nloc = b.st[0], nx = b.st[1];
;         if (nloc == 0u) { xcd_barrier_complete(bar, b.x, nloc, nx); b.st[0] = nloc; b.st[1] = nx; }
.LBB0_471:
	s_setprio 0
	s_add_i32 s90, s72, 2
	s_cmp_gt_i32 s90, s28
	s_cselect_b64 s[0:1], -1, 0
	s_cmp_lt_i32 s90, s29
	s_cselect_b64 s[4:5], -1, 0
	s_and_b64 s[0:1], s[0:1], s[4:5]
	s_andn2_b64 vcc, exec, s[0:1]
	s_cbranch_vccnz .LBB0_541
	s_cmp_lg_u32 s90, 1
	s_mov_b64 s[0:1], -1
	s_cbranch_scc0 .LBB0_524
	s_waitcnt vmcnt(0)
	v_readlane_b32 s0, v253, 3
	v_readlane_b32 s1, v253, 4
	s_andn2_b64 vcc, exec, s[0:1]
	s_waitcnt vmcnt(0) lgkmcnt(0)
	s_barrier
	s_cbranch_vccnz .LBB0_523
	v_cmp_eq_u32_e32 vcc, 0, v228
	s_and_saveexec_b64 s[0:1], vcc
	s_cbranch_execz .LBB0_522
	v_readlane_b32 s3, v254, 41
	s_waitcnt vmcnt(0) expcnt(0) lgkmcnt(0)
	s_nop 0
	v_mov_b32_e32 v0, s3
	ds_read_b32 v2, v0
	v_readlane_b32 s3, v254, 42
	s_waitcnt lgkmcnt(0)
	v_cmp_ne_u32_e32 vcc, 0, v2
	v_mov_b32_e32 v0, s3
	ds_read_b32 v0, v0
	s_cbranch_vccnz .LBB0_490
	s_mov_b32 s12, 1
	s_branch .LBB0_478
